# merge: the eight 2-byte gathers per token replaced by four 16-byte loads of the same span (wave-uniform dword/half select)
# speedup vs baseline: 1.0165x; 1.0098x over previous
.LBB0_1221:
	s_or_b64 exec, exec, s[10:11]
	s_cmpk_lt_i32 s2, 0x800
	s_cselect_b64 s[10:11], -1, 0
	s_and_b64 vcc, exec, s[10:11]
	s_waitcnt lgkmcnt(0)
	s_barrier
	s_cbranch_vccz .LBB0_1224
	v_readlane_b32 s46, v246, 38
	v_readlane_b32 s47, v246, 39
	v_readlane_b32 s48, v246, 40
	v_readlane_b32 s49, v246, 41
	v_lshrrev_b32_e32 v0, 6, v141
	v_and_b32_e32 v1, 63, v141
	s_mov_b32 s44, 0xbfb8aa3b
	v_readfirstlane_b32 s13, v0
	s_mov_b32 s45, 0xbfb8aa3b
	s_bitcmp1_b32 s13, 1
	s_cselect_b64 s[82:83], -1, 0
	s_bitcmp1_b32 s13, 0
	s_cselect_b32 s84, 0, 16
	v_lshlrev_b32_e32 v4, 4, v1
	v_lshrrev_b32_e32 v2, 3, v1
	v_lshlrev_b32_e32 v0, 5, v1
	v_lshlrev_b32_e32 v5, 2, v2
	v_mul_u32_u24_e32 v6, 0x318000, v2
	global_load_dwordx4 v[8:11], v0, s[46:47]
	global_load_dwordx4 v[12:15], v0, s[46:47] offset:16
	global_load_dwordx4 v[16:19], v0, s[48:49]
	global_load_dwordx4 v[20:23], v0, s[48:49] offset:16
	v_and_b32_e32 v7, 7, v1
	v_lshrrev_b32_e32 v2, 1, v7
	v_and_b32_e32 v7, 1, v7
	v_lshlrev_b32_e32 v2, 9, v2
	v_lshlrev_b32_e32 v7, 6, v7
	v_add3_u32 v7, v6, v2, v7
	v_mov_b32_e32 v100, 0x3a27c5ac
	v_and_b32_e32 v101, 15, v1
	v_lshlrev_b32_e32 v101, 2, v101
	s_add_i32 s16, s2, 0
	s_and_b32 s17, s16, 7
	s_lshr_b32 s12, s16, 3
	s_add_i32 s22, s90, 0
	s_lshr_b32 s22, s22, 3
	s_lshl_b32 s91, s17, 12
	s_add_i32 s91, s91, s13
	s_lshl_b32 s17, s17, 6
	s_add_i32 s17, s17, 0x4000
	s_add_u32 s74, s88, s17
	s_addc_u32 s75, s89, 0
	s_movk_i32 s56, 0x8000
	s_lshl_b32 s16, s12, 4
	s_add_i32 s16, s16, s91
	s_mul_i32 s17, s16, 0x2100
	s_add_u32 s24, s78, s17
	s_addc_u32 s25, s79, 0
	s_add_u32 s26, s24, 0x1900
	s_addc_u32 s27, s25, 0
	s_lshl_b32 s17, s16, 10
	s_add_u32 s28, s80, s17
	s_addc_u32 s29, s81, 0
	s_lshr_b32 s17, s16, 12
	s_lshl_b32 s17, s17, 11
	s_bfe_u32 s19, s16, 0x80004
	s_add_i32 s17, s17, s19
	s_mul_i32 s17, s17, 0x3180
	s_add_u32 s68, s86, s17
	s_addc_u32 s69, s87, 0
	s_and_b32 s19, s16, 15
	s_lshl_b32 s17, s19, 2
	s_addk_i32 s17, 0x3100
	s_add_u32 s30, s68, s17
	s_addc_u32 s31, s69, 0
	s_lshr_b32 s17, s19, 2
	s_lshl_b32 s17, s17, 7
	s_and_b32 s19, s19, 3
	s_mov_b32 s19, 0
	s_add_i32 s17, s17, s19
	s_addk_i32 s17, 0x2800
	s_add_u32 s70, s68, s17
	s_addc_u32 s71, s69, 0
	global_load_dword v24, v5, s[24:25] offset:3072
	global_load_dword v25, v5, s[24:25] offset:3104
	global_load_dword v26, v5, s[24:25] offset:3136
	global_load_dwordx4 v[28:31], v4, s[24:25]
	global_load_dwordx4 v[32:35], v4, s[24:25] offset:1024
	global_load_dwordx4 v[36:39], v4, s[24:25] offset:2048
	global_load_dwordx4 v[44:47], v4, s[26:27] offset:1024 nt
	global_load_dwordx4 v[48:51], v4, s[28:29]
	global_load_dwordx4 v[52:55], v4, s[26:27] nt
	global_load_dword v27, v6, s[30:31]
	global_load_dwordx4 v[172:175], v7, s[70:71]
	global_load_dwordx4 v[176:179], v7, s[70:71] offset:16
	global_load_dwordx4 v[180:183], v7, s[70:71] offset:32
	global_load_dwordx4 v[184:187], v7, s[70:71] offset:48
	s_mov_b32 s50, 1
.Lfm_loop:
	s_lshl_b32 s16, s12, 4
	s_add_i32 s16, s16, s91
	s_add_i32 s16, s16, 8
	s_mul_i32 s17, s16, 0x2100
	s_add_u32 s58, s78, s17
	s_addc_u32 s59, s79, 0
	s_add_u32 s60, s58, 0x1900
	s_addc_u32 s61, s59, 0
	s_lshl_b32 s17, s16, 10
	s_add_u32 s62, s80, s17
	s_addc_u32 s63, s81, 0
	s_lshr_b32 s17, s16, 12
	s_lshl_b32 s17, s17, 11
	s_bfe_u32 s19, s16, 0x80004
	s_add_i32 s17, s17, s19
	s_mul_i32 s17, s17, 0x3180
	s_add_u32 s68, s86, s17
	s_addc_u32 s69, s87, 0
	s_and_b32 s19, s16, 15
	s_lshl_b32 s17, s19, 2
	s_addk_i32 s17, 0x3100
	s_add_u32 s64, s68, s17
	s_addc_u32 s65, s69, 0
	s_lshr_b32 s17, s19, 2
	s_lshl_b32 s17, s17, 7
	s_and_b32 s19, s19, 3
	s_mov_b32 s19, 0
	s_add_i32 s17, s17, s19
	s_addk_i32 s17, 0x2800
	s_add_u32 s66, s68, s17
	s_addc_u32 s67, s69, 0
	global_load_dword v64, v5, s[58:59] offset:3072
	global_load_dword v65, v5, s[58:59] offset:3104
	global_load_dword v66, v5, s[58:59] offset:3136
	global_load_dwordx4 v[68:71], v4, s[58:59]
	global_load_dwordx4 v[72:75], v4, s[58:59] offset:1024
	global_load_dwordx4 v[76:79], v4, s[58:59] offset:2048
	global_load_dwordx4 v[80:83], v4, s[60:61] offset:1024 nt
	global_load_dwordx4 v[84:87], v4, s[62:63]
	global_load_dwordx4 v[88:91], v4, s[60:61] nt
	global_load_dword v67, v6, s[64:65]
	global_load_dwordx4 v[188:191], v7, s[66:67]
	global_load_dwordx4 v[192:195], v7, s[66:67] offset:16
	global_load_dwordx4 v[196:199], v7, s[66:67] offset:32
	global_load_dwordx4 v[200:203], v7, s[66:67] offset:48
	s_cmp_eq_u32 s50, 0
	s_cbranch_scc1 .Lfm_w20
	s_waitcnt vmcnt(14)
	s_branch .Lfm_wdone
.Lfm_w20:
	s_waitcnt vmcnt(16)
.Lfm_wdone:
	v_max3_f32 v127, v24, v25, v26
	v_sub_f32_e32 v102, v24, v127
	v_sub_f32_e32 v104, v25, v127
	v_sub_f32_e32 v106, v26, v127
	v_mul_f32_e32 v102, 0x3fb8aa3b, v102
	v_mul_f32_e32 v104, 0x3fb8aa3b, v104
	v_mul_f32_e32 v106, 0x3fb8aa3b, v106
	v_exp_f32_e32 v102, v102
	v_exp_f32_e32 v104, v104
	v_exp_f32_e32 v106, v106
	s_nop 0
	v_add_f32_e32 v127, v102, v104
	v_add_f32_e32 v127, v106, v127
	v_div_scale_f32 v122, s[72:73], v127, v127, 1.0
	v_rcp_f32_e32 v123, v122
	v_div_scale_f32 v124, vcc, 1.0, v127, 1.0
	v_fma_f32 v126, -v122, v123, 1.0
	v_fmac_f32_e32 v123, v126, v123
	v_mul_f32_e32 v125, v124, v123
	v_fma_f32 v126, -v122, v125, v124
	v_fmac_f32_e32 v125, v126, v123
	v_fma_f32 v122, -v122, v125, v124
	v_div_fmas_f32 v122, v122, v123, v125
	v_div_fixup_f32 v103, v122, v127, 1.0
	v_mul_f32_e32 v102, v102, v103
	v_mul_f32_e32 v104, v104, v103
	v_mul_f32_e32 v106, v106, v103
	v_lshlrev_b32_e32 v108, 16, v28
	v_and_b32_e32 v109, 0xffff0000, v28
	v_lshlrev_b32_e32 v110, 16, v32
	v_and_b32_e32 v111, 0xffff0000, v32
	v_lshlrev_b32_e32 v112, 16, v36
	v_and_b32_e32 v113, 0xffff0000, v36
	v_lshlrev_b32_e32 v114, 16, v44
	v_and_b32_e32 v115, 0xffff0000, v44
	v_pk_mul_f32 v[116:117], v[108:109], v[102:103] op_sel_hi:[1,0]
	v_pk_fma_f32 v[116:117], v[110:111], v[104:105], v[116:117] op_sel_hi:[1,0,1]
	v_pk_fma_f32 v[116:117], v[112:113], v[106:107], v[116:117] op_sel_hi:[1,0,1]
	v_pk_mul_f32 v[118:119], v[114:115], s[44:45]
	v_exp_f32_e32 v118, v118
	v_exp_f32_e32 v119, v119
	s_nop 0
	v_pk_add_f32 v[118:119], v[118:119], 1.0 op_sel_hi:[1,0]
	v_div_scale_f32 v122, s[72:73], v118, v118, v114
	v_rcp_f32_e32 v123, v122
	v_div_scale_f32 v124, vcc, v114, v118, v114
	v_fma_f32 v126, -v122, v123, 1.0
	v_fmac_f32_e32 v123, v126, v123
	v_mul_f32_e32 v125, v124, v123
	v_fma_f32 v126, -v122, v125, v124
	v_fmac_f32_e32 v125, v126, v123
	v_fma_f32 v122, -v122, v125, v124
	v_div_fmas_f32 v122, v122, v123, v125
	v_div_fixup_f32 v120, v122, v118, v114
	v_div_scale_f32 v122, s[72:73], v119, v119, v115
	v_rcp_f32_e32 v123, v122
	v_div_scale_f32 v124, vcc, v115, v119, v115
	v_fma_f32 v126, -v122, v123, 1.0
	v_fmac_f32_e32 v123, v126, v123
	v_mul_f32_e32 v125, v124, v123
	v_fma_f32 v126, -v122, v125, v124
	v_fmac_f32_e32 v125, v126, v123
	v_fma_f32 v122, -v122, v125, v124
	v_div_fmas_f32 v122, v122, v123, v125
	v_div_fixup_f32 v121, v122, v119, v115
	v_pk_mul_f32 v[116:117], v[120:121], v[116:117]
	v_cvt_pk_bf16_f32 v128, v116, v117
	v_lshlrev_b32_e32 v108, 16, v29
	v_and_b32_e32 v109, 0xffff0000, v29
	v_lshlrev_b32_e32 v110, 16, v33
	v_and_b32_e32 v111, 0xffff0000, v33
	v_lshlrev_b32_e32 v112, 16, v37
	v_and_b32_e32 v113, 0xffff0000, v37
	v_lshlrev_b32_e32 v114, 16, v45
	v_and_b32_e32 v115, 0xffff0000, v45
	v_pk_mul_f32 v[116:117], v[108:109], v[102:103] op_sel_hi:[1,0]
	v_pk_fma_f32 v[116:117], v[110:111], v[104:105], v[116:117] op_sel_hi:[1,0,1]
	v_pk_fma_f32 v[116:117], v[112:113], v[106:107], v[116:117] op_sel_hi:[1,0,1]
	v_pk_mul_f32 v[118:119], v[114:115], s[44:45]
	v_exp_f32_e32 v118, v118
	v_exp_f32_e32 v119, v119
	s_nop 0
	v_pk_add_f32 v[118:119], v[118:119], 1.0 op_sel_hi:[1,0]
	v_div_scale_f32 v122, s[72:73], v118, v118, v114
	v_rcp_f32_e32 v123, v122
	v_div_scale_f32 v124, vcc, v114, v118, v114
	v_fma_f32 v126, -v122, v123, 1.0
	v_fmac_f32_e32 v123, v126, v123
	v_mul_f32_e32 v125, v124, v123
	v_fma_f32 v126, -v122, v125, v124
	v_fmac_f32_e32 v125, v126, v123
	v_fma_f32 v122, -v122, v125, v124
	v_div_fmas_f32 v122, v122, v123, v125
	v_div_fixup_f32 v120, v122, v118, v114
	v_div_scale_f32 v122, s[72:73], v119, v119, v115
	v_rcp_f32_e32 v123, v122
	v_div_scale_f32 v124, vcc, v115, v119, v115
	v_fma_f32 v126, -v122, v123, 1.0
	v_fmac_f32_e32 v123, v126, v123
	v_mul_f32_e32 v125, v124, v123
	v_fma_f32 v126, -v122, v125, v124
	v_fmac_f32_e32 v125, v126, v123
	v_fma_f32 v122, -v122, v125, v124
	v_div_fmas_f32 v122, v122, v123, v125
	v_div_fixup_f32 v121, v122, v119, v115
	v_pk_mul_f32 v[116:117], v[120:121], v[116:117]
	v_cvt_pk_bf16_f32 v129, v116, v117
	v_lshlrev_b32_e32 v108, 16, v30
	v_and_b32_e32 v109, 0xffff0000, v30
	v_lshlrev_b32_e32 v110, 16, v34
	v_and_b32_e32 v111, 0xffff0000, v34
	v_lshlrev_b32_e32 v112, 16, v38
	v_and_b32_e32 v113, 0xffff0000, v38
	v_lshlrev_b32_e32 v114, 16, v46
	v_and_b32_e32 v115, 0xffff0000, v46
	v_pk_mul_f32 v[116:117], v[108:109], v[102:103] op_sel_hi:[1,0]
	v_pk_fma_f32 v[116:117], v[110:111], v[104:105], v[116:117] op_sel_hi:[1,0,1]
	v_pk_fma_f32 v[116:117], v[112:113], v[106:107], v[116:117] op_sel_hi:[1,0,1]
	v_pk_mul_f32 v[118:119], v[114:115], s[44:45]
	v_exp_f32_e32 v118, v118
	v_exp_f32_e32 v119, v119
	s_nop 0
	v_pk_add_f32 v[118:119], v[118:119], 1.0 op_sel_hi:[1,0]
	v_div_scale_f32 v122, s[72:73], v118, v118, v114
	v_rcp_f32_e32 v123, v122
	v_div_scale_f32 v124, vcc, v114, v118, v114
	v_fma_f32 v126, -v122, v123, 1.0
	v_fmac_f32_e32 v123, v126, v123
	v_mul_f32_e32 v125, v124, v123
	v_fma_f32 v126, -v122, v125, v124
	v_fmac_f32_e32 v125, v126, v123
	v_fma_f32 v122, -v122, v125, v124
	v_div_fmas_f32 v122, v122, v123, v125
	v_div_fixup_f32 v120, v122, v118, v114
	v_div_scale_f32 v122, s[72:73], v119, v119, v115
	v_rcp_f32_e32 v123, v122
	v_div_scale_f32 v124, vcc, v115, v119, v115
	v_fma_f32 v126, -v122, v123, 1.0
	v_fmac_f32_e32 v123, v126, v123
	v_mul_f32_e32 v125, v124, v123
	v_fma_f32 v126, -v122, v125, v124
	v_fmac_f32_e32 v125, v126, v123
	v_fma_f32 v122, -v122, v125, v124
	v_div_fmas_f32 v122, v122, v123, v125
	v_div_fixup_f32 v121, v122, v119, v115
	v_pk_mul_f32 v[116:117], v[120:121], v[116:117]
	v_cvt_pk_bf16_f32 v130, v116, v117
	v_lshlrev_b32_e32 v108, 16, v31
	v_and_b32_e32 v109, 0xffff0000, v31
	v_lshlrev_b32_e32 v110, 16, v35
	v_and_b32_e32 v111, 0xffff0000, v35
	v_lshlrev_b32_e32 v112, 16, v39
	v_and_b32_e32 v113, 0xffff0000, v39
	v_lshlrev_b32_e32 v114, 16, v47
	v_and_b32_e32 v115, 0xffff0000, v47
	v_pk_mul_f32 v[116:117], v[108:109], v[102:103] op_sel_hi:[1,0]
	v_pk_fma_f32 v[116:117], v[110:111], v[104:105], v[116:117] op_sel_hi:[1,0,1]
	v_pk_fma_f32 v[116:117], v[112:113], v[106:107], v[116:117] op_sel_hi:[1,0,1]
	v_pk_mul_f32 v[118:119], v[114:115], s[44:45]
	v_exp_f32_e32 v118, v118
	v_exp_f32_e32 v119, v119
	s_nop 0
	v_pk_add_f32 v[118:119], v[118:119], 1.0 op_sel_hi:[1,0]
	v_div_scale_f32 v122, s[72:73], v118, v118, v114
	v_rcp_f32_e32 v123, v122
	v_div_scale_f32 v124, vcc, v114, v118, v114
	v_fma_f32 v126, -v122, v123, 1.0
	v_fmac_f32_e32 v123, v126, v123
	v_mul_f32_e32 v125, v124, v123
	v_fma_f32 v126, -v122, v125, v124
	v_fmac_f32_e32 v125, v126, v123
	v_fma_f32 v122, -v122, v125, v124
	v_div_fmas_f32 v122, v122, v123, v125
	v_div_fixup_f32 v120, v122, v118, v114
	v_div_scale_f32 v122, s[72:73], v119, v119, v115
	v_rcp_f32_e32 v123, v122
	v_div_scale_f32 v124, vcc, v115, v119, v115
	v_fma_f32 v126, -v122, v123, 1.0
	v_fmac_f32_e32 v123, v126, v123
	v_mul_f32_e32 v125, v124, v123
	v_fma_f32 v126, -v122, v125, v124
	v_fmac_f32_e32 v125, v126, v123
	v_fma_f32 v122, -v122, v125, v124
	v_div_fmas_f32 v122, v122, v123, v125
	v_div_fixup_f32 v121, v122, v119, v115
	v_pk_mul_f32 v[116:117], v[120:121], v[116:117]
	v_cvt_pk_bf16_f32 v131, v116, v117
	global_store_dwordx4 v4, v[128:131], s[26:27] offset:1024
	v_lshlrev_b32_e32 v28, 16, v48
	v_and_b32_e32 v29, 0xffff0000, v48
	v_lshlrev_b32_e32 v30, 16, v49
	v_and_b32_e32 v31, 0xffff0000, v49
	v_lshlrev_b32_e32 v32, 16, v50
	v_and_b32_e32 v33, 0xffff0000, v50
	v_lshlrev_b32_e32 v34, 16, v51
	v_and_b32_e32 v35, 0xffff0000, v51
	v_lshlrev_b32_e32 v36, 16, v52
	v_and_b32_e32 v37, 0xffff0000, v52
	v_lshlrev_b32_e32 v38, 16, v53
	v_and_b32_e32 v39, 0xffff0000, v53
	v_lshlrev_b32_e32 v44, 16, v54
	v_and_b32_e32 v45, 0xffff0000, v54
	v_lshlrev_b32_e32 v46, 16, v55
	v_and_b32_e32 v47, 0xffff0000, v55
	v_cndmask_b32_e64 v56, v172, v173, s[82:83]
	v_cndmask_b32_e64 v57, v174, v175, s[82:83]
	v_cndmask_b32_e64 v58, v176, v177, s[82:83]
	v_cndmask_b32_e64 v59, v178, v179, s[82:83]
	v_cndmask_b32_e64 v60, v180, v181, s[82:83]
	v_cndmask_b32_e64 v61, v182, v183, s[82:83]
	v_cndmask_b32_e64 v62, v184, v185, s[82:83]
	v_cndmask_b32_e64 v63, v186, v187, s[82:83]
	v_lshlrev_b32_e32 v56, s84, v56
	v_lshlrev_b32_e32 v57, s84, v57
	v_lshlrev_b32_e32 v58, s84, v58
	v_lshlrev_b32_e32 v59, s84, v59
	v_lshlrev_b32_e32 v60, s84, v60
	v_lshlrev_b32_e32 v61, s84, v61
	v_lshlrev_b32_e32 v62, s84, v62
	v_lshlrev_b32_e32 v63, s84, v63
	v_and_b32_e32 v56, 0xffff0000, v56
	v_and_b32_e32 v57, 0xffff0000, v57
	v_and_b32_e32 v58, 0xffff0000, v58
	v_and_b32_e32 v59, 0xffff0000, v59
	v_and_b32_e32 v60, 0xffff0000, v60
	v_and_b32_e32 v61, 0xffff0000, v61
	v_and_b32_e32 v62, 0xffff0000, v62
	v_and_b32_e32 v63, 0xffff0000, v63
	v_add_f32_e32 v108, v28, v29
	v_add_f32_e32 v108, v108, v30
	v_add_f32_e32 v108, v108, v31
	v_add_f32_e32 v108, v108, v32
	v_add_f32_e32 v108, v108, v33
	v_add_f32_e32 v108, v108, v34
	v_add_f32_e32 v108, v108, v35
	s_nop 1
	v_add_f32_dpp v109, v108, v108 quad_perm:[1,0,3,2] row_mask:0xf bank_mask:0xf
	s_nop 1
	v_add_f32_dpp v108, v109, v109 quad_perm:[2,3,0,1] row_mask:0xf bank_mask:0xf
	s_nop 1
	v_add_f32_dpp v109, v108, v108 row_half_mirror row_mask:0xf bank_mask:0xf
	v_mov_b32_e32 v108, v109
	v_mul_f32_e32 v108, 0x3c800000, v108
	v_pk_add_f32 v[28:29], v[28:29], v[108:109] op_sel_hi:[1,0] neg_lo:[0,1] neg_hi:[0,1]
	v_pk_add_f32 v[30:31], v[30:31], v[108:109] op_sel_hi:[1,0] neg_lo:[0,1] neg_hi:[0,1]
	v_pk_add_f32 v[32:33], v[32:33], v[108:109] op_sel_hi:[1,0] neg_lo:[0,1] neg_hi:[0,1]
	v_pk_add_f32 v[34:35], v[34:35], v[108:109] op_sel_hi:[1,0] neg_lo:[0,1] neg_hi:[0,1]
	v_pk_mul_f32 v[110:111], v[28:29], v[28:29]
	v_pk_mul_f32 v[112:113], v[30:31], v[30:31]
	v_pk_mul_f32 v[114:115], v[32:33], v[32:33]
	v_pk_mul_f32 v[116:117], v[34:35], v[34:35]
	v_add_f32_e32 v118, v110, v111
	v_add_f32_e32 v118, v112, v118
	v_add_f32_e32 v118, v113, v118
	v_add_f32_e32 v118, v114, v118
	v_add_f32_e32 v118, v115, v118
	v_add_f32_e32 v118, v116, v118
	v_add_f32_e32 v118, v117, v118
	s_nop 1
	v_add_f32_dpp v119, v118, v118 quad_perm:[1,0,3,2] row_mask:0xf bank_mask:0xf
	s_nop 1
	v_add_f32_dpp v118, v119, v119 quad_perm:[2,3,0,1] row_mask:0xf bank_mask:0xf
	s_nop 1
	v_add_f32_dpp v119, v118, v118 row_half_mirror row_mask:0xf bank_mask:0xf
	v_mov_b32_e32 v118, v119
	v_fmamk_f32 v118, v118, 0x3c800000, v100
	v_rsq_f32_e32 v118, v118
	v_mov_b32_e32 v120, v27
	v_pk_mul_f32 v[28:29], v[28:29], v[118:119] op_sel_hi:[1,0]
	v_pk_mul_f32 v[30:31], v[30:31], v[118:119] op_sel_hi:[1,0]
	v_pk_mul_f32 v[32:33], v[32:33], v[118:119] op_sel_hi:[1,0]
	v_pk_mul_f32 v[34:35], v[34:35], v[118:119] op_sel_hi:[1,0]
	v_pk_fma_f32 v[28:29], v[8:9], v[28:29], v[16:17]
	v_pk_fma_f32 v[30:31], v[10:11], v[30:31], v[18:19]
	v_pk_fma_f32 v[32:33], v[12:13], v[32:33], v[20:21]
	v_pk_fma_f32 v[34:35], v[14:15], v[34:35], v[22:23]
	v_pk_fma_f32 v[28:29], v[120:121], v[56:57], v[28:29] op_sel_hi:[0,1,1]
	v_pk_fma_f32 v[30:31], v[120:121], v[58:59], v[30:31] op_sel_hi:[0,1,1]
	v_pk_fma_f32 v[32:33], v[120:121], v[60:61], v[32:33] op_sel_hi:[0,1,1]
	v_pk_fma_f32 v[34:35], v[120:121], v[62:63], v[34:35] op_sel_hi:[0,1,1]
	v_pk_mul_f32 v[118:119], v[36:37], s[44:45]
	v_exp_f32_e32 v118, v118
	v_exp_f32_e32 v119, v119
	s_nop 0
	v_pk_add_f32 v[118:119], v[118:119], 1.0 op_sel_hi:[1,0]
	v_div_scale_f32 v122, s[72:73], v118, v118, v36
	v_rcp_f32_e32 v123, v122
	v_div_scale_f32 v124, vcc, v36, v118, v36
	v_fma_f32 v126, -v122, v123, 1.0
	v_fmac_f32_e32 v123, v126, v123
	v_mul_f32_e32 v125, v124, v123
	v_fma_f32 v126, -v122, v125, v124
	v_fmac_f32_e32 v125, v126, v123
	v_fma_f32 v122, -v122, v125, v124
	v_div_fmas_f32 v122, v122, v123, v125
	v_div_fixup_f32 v108, v122, v118, v36
	v_div_scale_f32 v122, s[72:73], v119, v119, v37
	v_rcp_f32_e32 v123, v122
	v_div_scale_f32 v124, vcc, v37, v119, v37
	v_fma_f32 v126, -v122, v123, 1.0
	v_fmac_f32_e32 v123, v126, v123
	v_mul_f32_e32 v125, v124, v123
	v_fma_f32 v126, -v122, v125, v124
	v_fmac_f32_e32 v125, v126, v123
	v_fma_f32 v122, -v122, v125, v124
	v_div_fmas_f32 v122, v122, v123, v125
	v_div_fixup_f32 v109, v122, v119, v37
	v_pk_mul_f32 v[28:29], v[108:109], v[28:29]
	v_cvt_pk_bf16_f32 v132, v28, v29
	v_pk_mul_f32 v[118:119], v[38:39], s[44:45]
	v_exp_f32_e32 v118, v118
	v_exp_f32_e32 v119, v119
	s_nop 0
	v_pk_add_f32 v[118:119], v[118:119], 1.0 op_sel_hi:[1,0]
	v_div_scale_f32 v122, s[72:73], v118, v118, v38
	v_rcp_f32_e32 v123, v122
	v_div_scale_f32 v124, vcc, v38, v118, v38
	v_fma_f32 v126, -v122, v123, 1.0
	v_fmac_f32_e32 v123, v126, v123
	v_mul_f32_e32 v125, v124, v123
	v_fma_f32 v126, -v122, v125, v124
	v_fmac_f32_e32 v125, v126, v123
	v_fma_f32 v122, -v122, v125, v124
	v_div_fmas_f32 v122, v122, v123, v125
	v_div_fixup_f32 v108, v122, v118, v38
	v_div_scale_f32 v122, s[72:73], v119, v119, v39
	v_rcp_f32_e32 v123, v122
	v_div_scale_f32 v124, vcc, v39, v119, v39
	v_fma_f32 v126, -v122, v123, 1.0
	v_fmac_f32_e32 v123, v126, v123
	v_mul_f32_e32 v125, v124, v123
	v_fma_f32 v126, -v122, v125, v124
	v_fmac_f32_e32 v125, v126, v123
	v_fma_f32 v122, -v122, v125, v124
	v_div_fmas_f32 v122, v122, v123, v125
	v_div_fixup_f32 v109, v122, v119, v39
	v_pk_mul_f32 v[30:31], v[108:109], v[30:31]
	v_cvt_pk_bf16_f32 v133, v30, v31
	v_pk_mul_f32 v[118:119], v[44:45], s[44:45]
	v_exp_f32_e32 v118, v118
	v_exp_f32_e32 v119, v119
	s_nop 0
	v_pk_add_f32 v[118:119], v[118:119], 1.0 op_sel_hi:[1,0]
	v_div_scale_f32 v122, s[72:73], v118, v118, v44
	v_rcp_f32_e32 v123, v122
	v_div_scale_f32 v124, vcc, v44, v118, v44
	v_fma_f32 v126, -v122, v123, 1.0
	v_fmac_f32_e32 v123, v126, v123
	v_mul_f32_e32 v125, v124, v123
	v_fma_f32 v126, -v122, v125, v124
	v_fmac_f32_e32 v125, v126, v123
	v_fma_f32 v122, -v122, v125, v124
	v_div_fmas_f32 v122, v122, v123, v125
	v_div_fixup_f32 v108, v122, v118, v44
	v_div_scale_f32 v122, s[72:73], v119, v119, v45
	v_rcp_f32_e32 v123, v122
	v_div_scale_f32 v124, vcc, v45, v119, v45
	v_fma_f32 v126, -v122, v123, 1.0
	v_fmac_f32_e32 v123, v126, v123
	v_mul_f32_e32 v125, v124, v123
	v_fma_f32 v126, -v122, v125, v124
	v_fmac_f32_e32 v125, v126, v123
	v_fma_f32 v122, -v122, v125, v124
	v_div_fmas_f32 v122, v122, v123, v125
	v_div_fixup_f32 v109, v122, v119, v45
	v_pk_mul_f32 v[32:33], v[108:109], v[32:33]
	v_cvt_pk_bf16_f32 v134, v32, v33
	v_pk_mul_f32 v[118:119], v[46:47], s[44:45]
	v_exp_f32_e32 v118, v118
	v_exp_f32_e32 v119, v119
	s_nop 0
	v_pk_add_f32 v[118:119], v[118:119], 1.0 op_sel_hi:[1,0]
	v_div_scale_f32 v122, s[72:73], v118, v118, v46
	v_rcp_f32_e32 v123, v122
	v_div_scale_f32 v124, vcc, v46, v118, v46
	v_fma_f32 v126, -v122, v123, 1.0
	v_fmac_f32_e32 v123, v126, v123
	v_mul_f32_e32 v125, v124, v123
	v_fma_f32 v126, -v122, v125, v124
	v_fmac_f32_e32 v125, v126, v123
	v_fma_f32 v122, -v122, v125, v124
	v_div_fmas_f32 v122, v122, v123, v125
	v_div_fixup_f32 v108, v122, v118, v46
	v_div_scale_f32 v122, s[72:73], v119, v119, v47
	v_rcp_f32_e32 v123, v122
	v_div_scale_f32 v124, vcc, v47, v119, v47
	v_fma_f32 v126, -v122, v123, 1.0
	v_fmac_f32_e32 v123, v126, v123
	v_mul_f32_e32 v125, v124, v123
	v_fma_f32 v126, -v122, v125, v124
	v_fmac_f32_e32 v125, v126, v123
	v_fma_f32 v122, -v122, v125, v124
	v_div_fmas_f32 v122, v122, v123, v125
	v_div_fixup_f32 v109, v122, v119, v47
	v_pk_mul_f32 v[34:35], v[108:109], v[34:35]
	v_cvt_pk_bf16_f32 v135, v34, v35
	global_store_dwordx4 v4, v[132:135], s[26:27]
	s_mov_b32 s50, 0
	s_add_i32 s12, s12, s22
	s_cmpk_lt_i32 s12, 0x100
	s_cbranch_scc0 .Lfm_nonext
	s_lshl_b32 s16, s12, 4
	s_add_i32 s16, s16, s91
	s_mul_i32 s17, s16, 0x2100
	s_add_u32 s24, s78, s17
	s_addc_u32 s25, s79, 0
	s_add_u32 s26, s24, 0x1900
	s_addc_u32 s27, s25, 0
	s_lshl_b32 s17, s16, 10
	s_add_u32 s28, s80, s17
	s_addc_u32 s29, s81, 0
	s_lshr_b32 s17, s16, 12
	s_lshl_b32 s17, s17, 11
	s_bfe_u32 s19, s16, 0x80004
	s_add_i32 s17, s17, s19
	s_mul_i32 s17, s17, 0x3180
	s_add_u32 s68, s86, s17
	s_addc_u32 s69, s87, 0
	s_and_b32 s19, s16, 15
	s_lshl_b32 s17, s19, 2
	s_addk_i32 s17, 0x3100
	s_add_u32 s30, s68, s17
	s_addc_u32 s31, s69, 0
	s_lshr_b32 s17, s19, 2
	s_lshl_b32 s17, s17, 7
	s_and_b32 s19, s19, 3
	s_mov_b32 s19, 0
	s_add_i32 s17, s17, s19
	s_addk_i32 s17, 0x2800
	s_add_u32 s70, s68, s17
	s_addc_u32 s71, s69, 0
	global_load_dword v24, v5, s[24:25] offset:3072
	global_load_dword v25, v5, s[24:25] offset:3104
	global_load_dword v26, v5, s[24:25] offset:3136
	global_load_dwordx4 v[28:31], v4, s[24:25]
	global_load_dwordx4 v[32:35], v4, s[24:25] offset:1024
	global_load_dwordx4 v[36:39], v4, s[24:25] offset:2048
	global_load_dwordx4 v[44:47], v4, s[26:27] offset:1024 nt
	global_load_dwordx4 v[48:51], v4, s[28:29]
	global_load_dwordx4 v[52:55], v4, s[26:27] nt
	global_load_dword v27, v6, s[30:31]
	global_load_dwordx4 v[172:175], v7, s[70:71]
	global_load_dwordx4 v[176:179], v7, s[70:71] offset:16
	global_load_dwordx4 v[180:183], v7, s[70:71] offset:32
	global_load_dwordx4 v[184:187], v7, s[70:71] offset:48
	s_waitcnt vmcnt(16)
	s_branch .Lfm_cb

.Lfm_cb:
	v_max3_f32 v127, v64, v65, v66
	v_sub_f32_e32 v102, v64, v127
	v_sub_f32_e32 v104, v65, v127
	v_sub_f32_e32 v106, v66, v127
	v_mul_f32_e32 v102, 0x3fb8aa3b, v102
	v_mul_f32_e32 v104, 0x3fb8aa3b, v104
	v_mul_f32_e32 v106, 0x3fb8aa3b, v106
	v_exp_f32_e32 v102, v102
	v_exp_f32_e32 v104, v104
	v_exp_f32_e32 v106, v106
	s_nop 0
	v_add_f32_e32 v127, v102, v104
	v_add_f32_e32 v127, v106, v127
	v_div_scale_f32 v122, s[72:73], v127, v127, 1.0
	v_rcp_f32_e32 v123, v122
	v_div_scale_f32 v124, vcc, 1.0, v127, 1.0
	v_fma_f32 v126, -v122, v123, 1.0
	v_fmac_f32_e32 v123, v126, v123
	v_mul_f32_e32 v125, v124, v123
	v_fma_f32 v126, -v122, v125, v124
	v_fmac_f32_e32 v125, v126, v123
	v_fma_f32 v122, -v122, v125, v124
	v_div_fmas_f32 v122, v122, v123, v125
	v_div_fixup_f32 v103, v122, v127, 1.0
	v_mul_f32_e32 v102, v102, v103
	v_mul_f32_e32 v104, v104, v103
	v_mul_f32_e32 v106, v106, v103
	v_lshlrev_b32_e32 v108, 16, v68
	v_and_b32_e32 v109, 0xffff0000, v68
	v_lshlrev_b32_e32 v110, 16, v72
	v_and_b32_e32 v111, 0xffff0000, v72
	v_lshlrev_b32_e32 v112, 16, v76
	v_and_b32_e32 v113, 0xffff0000, v76
	v_lshlrev_b32_e32 v114, 16, v80
	v_and_b32_e32 v115, 0xffff0000, v80
	v_pk_mul_f32 v[116:117], v[108:109], v[102:103] op_sel_hi:[1,0]
	v_pk_fma_f32 v[116:117], v[110:111], v[104:105], v[116:117] op_sel_hi:[1,0,1]
	v_pk_fma_f32 v[116:117], v[112:113], v[106:107], v[116:117] op_sel_hi:[1,0,1]
	v_pk_mul_f32 v[118:119], v[114:115], s[44:45]
	v_exp_f32_e32 v118, v118
	v_exp_f32_e32 v119, v119
	s_nop 0
	v_pk_add_f32 v[118:119], v[118:119], 1.0 op_sel_hi:[1,0]
	v_div_scale_f32 v122, s[72:73], v118, v118, v114
	v_rcp_f32_e32 v123, v122
	v_div_scale_f32 v124, vcc, v114, v118, v114
	v_fma_f32 v126, -v122, v123, 1.0
	v_fmac_f32_e32 v123, v126, v123
	v_mul_f32_e32 v125, v124, v123
	v_fma_f32 v126, -v122, v125, v124
	v_fmac_f32_e32 v125, v126, v123
	v_fma_f32 v122, -v122, v125, v124
	v_div_fmas_f32 v122, v122, v123, v125
	v_div_fixup_f32 v120, v122, v118, v114
	v_div_scale_f32 v122, s[72:73], v119, v119, v115
	v_rcp_f32_e32 v123, v122
	v_div_scale_f32 v124, vcc, v115, v119, v115
	v_fma_f32 v126, -v122, v123, 1.0
	v_fmac_f32_e32 v123, v126, v123
	v_mul_f32_e32 v125, v124, v123
	v_fma_f32 v126, -v122, v125, v124
	v_fmac_f32_e32 v125, v126, v123
	v_fma_f32 v122, -v122, v125, v124
	v_div_fmas_f32 v122, v122, v123, v125
	v_div_fixup_f32 v121, v122, v119, v115
	v_pk_mul_f32 v[116:117], v[120:121], v[116:117]
	v_cvt_pk_bf16_f32 v128, v116, v117
	v_lshlrev_b32_e32 v108, 16, v69
	v_and_b32_e32 v109, 0xffff0000, v69
	v_lshlrev_b32_e32 v110, 16, v73
	v_and_b32_e32 v111, 0xffff0000, v73
	v_lshlrev_b32_e32 v112, 16, v77
	v_and_b32_e32 v113, 0xffff0000, v77
	v_lshlrev_b32_e32 v114, 16, v81
	v_and_b32_e32 v115, 0xffff0000, v81
	v_pk_mul_f32 v[116:117], v[108:109], v[102:103] op_sel_hi:[1,0]
	v_pk_fma_f32 v[116:117], v[110:111], v[104:105], v[116:117] op_sel_hi:[1,0,1]
	v_pk_fma_f32 v[116:117], v[112:113], v[106:107], v[116:117] op_sel_hi:[1,0,1]
	v_pk_mul_f32 v[118:119], v[114:115], s[44:45]
	v_exp_f32_e32 v118, v118
	v_exp_f32_e32 v119, v119
	s_nop 0
	v_pk_add_f32 v[118:119], v[118:119], 1.0 op_sel_hi:[1,0]
	v_div_scale_f32 v122, s[72:73], v118, v118, v114
	v_rcp_f32_e32 v123, v122
	v_div_scale_f32 v124, vcc, v114, v118, v114
	v_fma_f32 v126, -v122, v123, 1.0
	v_fmac_f32_e32 v123, v126, v123
	v_mul_f32_e32 v125, v124, v123
	v_fma_f32 v126, -v122, v125, v124
	v_fmac_f32_e32 v125, v126, v123
	v_fma_f32 v122, -v122, v125, v124
	v_div_fmas_f32 v122, v122, v123, v125
	v_div_fixup_f32 v120, v122, v118, v114
	v_div_scale_f32 v122, s[72:73], v119, v119, v115
	v_rcp_f32_e32 v123, v122
	v_div_scale_f32 v124, vcc, v115, v119, v115
	v_fma_f32 v126, -v122, v123, 1.0
	v_fmac_f32_e32 v123, v126, v123
	v_mul_f32_e32 v125, v124, v123
	v_fma_f32 v126, -v122, v125, v124
	v_fmac_f32_e32 v125, v126, v123
	v_fma_f32 v122, -v122, v125, v124
	v_div_fmas_f32 v122, v122, v123, v125
	v_div_fixup_f32 v121, v122, v119, v115
	v_pk_mul_f32 v[116:117], v[120:121], v[116:117]
	v_cvt_pk_bf16_f32 v129, v116, v117
	v_lshlrev_b32_e32 v108, 16, v70
	v_and_b32_e32 v109, 0xffff0000, v70
	v_lshlrev_b32_e32 v110, 16, v74
	v_and_b32_e32 v111, 0xffff0000, v74
	v_lshlrev_b32_e32 v112, 16, v78
	v_and_b32_e32 v113, 0xffff0000, v78
	v_lshlrev_b32_e32 v114, 16, v82
	v_and_b32_e32 v115, 0xffff0000, v82
	v_pk_mul_f32 v[116:117], v[108:109], v[102:103] op_sel_hi:[1,0]
	v_pk_fma_f32 v[116:117], v[110:111], v[104:105], v[116:117] op_sel_hi:[1,0,1]
	v_pk_fma_f32 v[116:117], v[112:113], v[106:107], v[116:117] op_sel_hi:[1,0,1]
	v_pk_mul_f32 v[118:119], v[114:115], s[44:45]
	v_exp_f32_e32 v118, v118
	v_exp_f32_e32 v119, v119
	s_nop 0
	v_pk_add_f32 v[118:119], v[118:119], 1.0 op_sel_hi:[1,0]
	v_div_scale_f32 v122, s[72:73], v118, v118, v114
	v_rcp_f32_e32 v123, v122
	v_div_scale_f32 v124, vcc, v114, v118, v114
	v_fma_f32 v126, -v122, v123, 1.0
	v_fmac_f32_e32 v123, v126, v123
	v_mul_f32_e32 v125, v124, v123
	v_fma_f32 v126, -v122, v125, v124
	v_fmac_f32_e32 v125, v126, v123
	v_fma_f32 v122, -v122, v125, v124
	v_div_fmas_f32 v122, v122, v123, v125
	v_div_fixup_f32 v120, v122, v118, v114
	v_div_scale_f32 v122, s[72:73], v119, v119, v115
	v_rcp_f32_e32 v123, v122
	v_div_scale_f32 v124, vcc, v115, v119, v115
	v_fma_f32 v126, -v122, v123, 1.0
	v_fmac_f32_e32 v123, v126, v123
	v_mul_f32_e32 v125, v124, v123
	v_fma_f32 v126, -v122, v125, v124
	v_fmac_f32_e32 v125, v126, v123
	v_fma_f32 v122, -v122, v125, v124
	v_div_fmas_f32 v122, v122, v123, v125
	v_div_fixup_f32 v121, v122, v119, v115
	v_pk_mul_f32 v[116:117], v[120:121], v[116:117]
	v_cvt_pk_bf16_f32 v130, v116, v117
	v_lshlrev_b32_e32 v108, 16, v71
	v_and_b32_e32 v109, 0xffff0000, v71
	v_lshlrev_b32_e32 v110, 16, v75
	v_and_b32_e32 v111, 0xffff0000, v75
	v_lshlrev_b32_e32 v112, 16, v79
	v_and_b32_e32 v113, 0xffff0000, v79
	v_lshlrev_b32_e32 v114, 16, v83
	v_and_b32_e32 v115, 0xffff0000, v83
	v_pk_mul_f32 v[116:117], v[108:109], v[102:103] op_sel_hi:[1,0]
	v_pk_fma_f32 v[116:117], v[110:111], v[104:105], v[116:117] op_sel_hi:[1,0,1]
	v_pk_fma_f32 v[116:117], v[112:113], v[106:107], v[116:117] op_sel_hi:[1,0,1]
	v_pk_mul_f32 v[118:119], v[114:115], s[44:45]
	v_exp_f32_e32 v118, v118
	v_exp_f32_e32 v119, v119
	s_nop 0
	v_pk_add_f32 v[118:119], v[118:119], 1.0 op_sel_hi:[1,0]
	v_div_scale_f32 v122, s[72:73], v118, v118, v114
	v_rcp_f32_e32 v123, v122
	v_div_scale_f32 v124, vcc, v114, v118, v114
	v_fma_f32 v126, -v122, v123, 1.0
	v_fmac_f32_e32 v123, v126, v123
	v_mul_f32_e32 v125, v124, v123
	v_fma_f32 v126, -v122, v125, v124
	v_fmac_f32_e32 v125, v126, v123
	v_fma_f32 v122, -v122, v125, v124
	v_div_fmas_f32 v122, v122, v123, v125
	v_div_fixup_f32 v120, v122, v118, v114
	v_div_scale_f32 v122, s[72:73], v119, v119, v115
	v_rcp_f32_e32 v123, v122
	v_div_scale_f32 v124, vcc, v115, v119, v115
	v_fma_f32 v126, -v122, v123, 1.0
	v_fmac_f32_e32 v123, v126, v123
	v_mul_f32_e32 v125, v124, v123
	v_fma_f32 v126, -v122, v125, v124
	v_fmac_f32_e32 v125, v126, v123
	v_fma_f32 v122, -v122, v125, v124
	v_div_fmas_f32 v122, v122, v123, v125
	v_div_fixup_f32 v121, v122, v119, v115
	v_pk_mul_f32 v[116:117], v[120:121], v[116:117]
	v_cvt_pk_bf16_f32 v131, v116, v117
	global_store_dwordx4 v4, v[128:131], s[60:61] offset:1024
	v_lshlrev_b32_e32 v68, 16, v84
	v_and_b32_e32 v69, 0xffff0000, v84
	v_lshlrev_b32_e32 v70, 16, v85
	v_and_b32_e32 v71, 0xffff0000, v85
	v_lshlrev_b32_e32 v72, 16, v86
	v_and_b32_e32 v73, 0xffff0000, v86
	v_lshlrev_b32_e32 v74, 16, v87
	v_and_b32_e32 v75, 0xffff0000, v87
	v_lshlrev_b32_e32 v76, 16, v88
	v_and_b32_e32 v77, 0xffff0000, v88
	v_lshlrev_b32_e32 v78, 16, v89
	v_and_b32_e32 v79, 0xffff0000, v89
	v_lshlrev_b32_e32 v80, 16, v90
	v_and_b32_e32 v81, 0xffff0000, v90
	v_lshlrev_b32_e32 v82, 16, v91
	v_and_b32_e32 v83, 0xffff0000, v91
	v_cndmask_b32_e64 v92, v188, v189, s[82:83]
	v_cndmask_b32_e64 v93, v190, v191, s[82:83]
	v_cndmask_b32_e64 v94, v192, v193, s[82:83]
	v_cndmask_b32_e64 v95, v194, v195, s[82:83]
	v_cndmask_b32_e64 v96, v196, v197, s[82:83]
	v_cndmask_b32_e64 v97, v198, v199, s[82:83]
	v_cndmask_b32_e64 v98, v200, v201, s[82:83]
	v_cndmask_b32_e64 v99, v202, v203, s[82:83]
	v_lshlrev_b32_e32 v92, s84, v92
	v_lshlrev_b32_e32 v93, s84, v93
	v_lshlrev_b32_e32 v94, s84, v94
	v_lshlrev_b32_e32 v95, s84, v95
	v_lshlrev_b32_e32 v96, s84, v96
	v_lshlrev_b32_e32 v97, s84, v97
	v_lshlrev_b32_e32 v98, s84, v98
	v_lshlrev_b32_e32 v99, s84, v99
	v_and_b32_e32 v92, 0xffff0000, v92
	v_and_b32_e32 v93, 0xffff0000, v93
	v_and_b32_e32 v94, 0xffff0000, v94
	v_and_b32_e32 v95, 0xffff0000, v95
	v_and_b32_e32 v96, 0xffff0000, v96
	v_and_b32_e32 v97, 0xffff0000, v97
	v_and_b32_e32 v98, 0xffff0000, v98
	v_and_b32_e32 v99, 0xffff0000, v99
	v_add_f32_e32 v108, v68, v69
	v_add_f32_e32 v108, v108, v70
	v_add_f32_e32 v108, v108, v71
	v_add_f32_e32 v108, v108, v72
	v_add_f32_e32 v108, v108, v73
	v_add_f32_e32 v108, v108, v74
	v_add_f32_e32 v108, v108, v75
	s_nop 1
	v_add_f32_dpp v109, v108, v108 quad_perm:[1,0,3,2] row_mask:0xf bank_mask:0xf
	s_nop 1
	v_add_f32_dpp v108, v109, v109 quad_perm:[2,3,0,1] row_mask:0xf bank_mask:0xf
	s_nop 1
	v_add_f32_dpp v109, v108, v108 row_half_mirror row_mask:0xf bank_mask:0xf
	v_mov_b32_e32 v108, v109
	v_mul_f32_e32 v108, 0x3c800000, v108
	v_pk_add_f32 v[68:69], v[68:69], v[108:109] op_sel_hi:[1,0] neg_lo:[0,1] neg_hi:[0,1]
	v_pk_add_f32 v[70:71], v[70:71], v[108:109] op_sel_hi:[1,0] neg_lo:[0,1] neg_hi:[0,1]
	v_pk_add_f32 v[72:73], v[72:73], v[108:109] op_sel_hi:[1,0] neg_lo:[0,1] neg_hi:[0,1]
	v_pk_add_f32 v[74:75], v[74:75], v[108:109] op_sel_hi:[1,0] neg_lo:[0,1] neg_hi:[0,1]
	v_pk_mul_f32 v[110:111], v[68:69], v[68:69]
	v_pk_mul_f32 v[112:113], v[70:71], v[70:71]
	v_pk_mul_f32 v[114:115], v[72:73], v[72:73]
	v_pk_mul_f32 v[116:117], v[74:75], v[74:75]
	v_add_f32_e32 v118, v110, v111
	v_add_f32_e32 v118, v112, v118
	v_add_f32_e32 v118, v113, v118
	v_add_f32_e32 v118, v114, v118
	v_add_f32_e32 v118, v115, v118
	v_add_f32_e32 v118, v116, v118
	v_add_f32_e32 v118, v117, v118
	s_nop 1
	v_add_f32_dpp v119, v118, v118 quad_perm:[1,0,3,2] row_mask:0xf bank_mask:0xf
	s_nop 1
	v_add_f32_dpp v118, v119, v119 quad_perm:[2,3,0,1] row_mask:0xf bank_mask:0xf
	s_nop 1
	v_add_f32_dpp v119, v118, v118 row_half_mirror row_mask:0xf bank_mask:0xf
	v_mov_b32_e32 v118, v119
	v_fmamk_f32 v118, v118, 0x3c800000, v100
	v_rsq_f32_e32 v118, v118
	v_mov_b32_e32 v120, v67
	v_pk_mul_f32 v[68:69], v[68:69], v[118:119] op_sel_hi:[1,0]
	v_pk_mul_f32 v[70:71], v[70:71], v[118:119] op_sel_hi:[1,0]
	v_pk_mul_f32 v[72:73], v[72:73], v[118:119] op_sel_hi:[1,0]
	v_pk_mul_f32 v[74:75], v[74:75], v[118:119] op_sel_hi:[1,0]
	v_pk_fma_f32 v[68:69], v[8:9], v[68:69], v[16:17]
	v_pk_fma_f32 v[70:71], v[10:11], v[70:71], v[18:19]
	v_pk_fma_f32 v[72:73], v[12:13], v[72:73], v[20:21]
	v_pk_fma_f32 v[74:75], v[14:15], v[74:75], v[22:23]
	v_pk_fma_f32 v[68:69], v[120:121], v[92:93], v[68:69] op_sel_hi:[0,1,1]
	v_pk_fma_f32 v[70:71], v[120:121], v[94:95], v[70:71] op_sel_hi:[0,1,1]
	v_pk_fma_f32 v[72:73], v[120:121], v[96:97], v[72:73] op_sel_hi:[0,1,1]
	v_pk_fma_f32 v[74:75], v[120:121], v[98:99], v[74:75] op_sel_hi:[0,1,1]
	v_pk_mul_f32 v[118:119], v[76:77], s[44:45]
	v_exp_f32_e32 v118, v118
	v_exp_f32_e32 v119, v119
	s_nop 0
	v_pk_add_f32 v[118:119], v[118:119], 1.0 op_sel_hi:[1,0]
	v_div_scale_f32 v122, s[72:73], v118, v118, v76
	v_rcp_f32_e32 v123, v122
	v_div_scale_f32 v124, vcc, v76, v118, v76
	v_fma_f32 v126, -v122, v123, 1.0
	v_fmac_f32_e32 v123, v126, v123
	v_mul_f32_e32 v125, v124, v123
	v_fma_f32 v126, -v122, v125, v124
	v_fmac_f32_e32 v125, v126, v123
	v_fma_f32 v122, -v122, v125, v124
	v_div_fmas_f32 v122, v122, v123, v125
	v_div_fixup_f32 v108, v122, v118, v76
	v_div_scale_f32 v122, s[72:73], v119, v119, v77
	v_rcp_f32_e32 v123, v122
	v_div_scale_f32 v124, vcc, v77, v119, v77
	v_fma_f32 v126, -v122, v123, 1.0
	v_fmac_f32_e32 v123, v126, v123
	v_mul_f32_e32 v125, v124, v123
	v_fma_f32 v126, -v122, v125, v124
	v_fmac_f32_e32 v125, v126, v123
	v_fma_f32 v122, -v122, v125, v124
	v_div_fmas_f32 v122, v122, v123, v125
	v_div_fixup_f32 v109, v122, v119, v77
	v_pk_mul_f32 v[68:69], v[108:109], v[68:69]
	v_cvt_pk_bf16_f32 v132, v68, v69
	v_pk_mul_f32 v[118:119], v[78:79], s[44:45]
	v_exp_f32_e32 v118, v118
	v_exp_f32_e32 v119, v119
	s_nop 0
	v_pk_add_f32 v[118:119], v[118:119], 1.0 op_sel_hi:[1,0]
	v_div_scale_f32 v122, s[72:73], v118, v118, v78
	v_rcp_f32_e32 v123, v122
	v_div_scale_f32 v124, vcc, v78, v118, v78
	v_fma_f32 v126, -v122, v123, 1.0
	v_fmac_f32_e32 v123, v126, v123
	v_mul_f32_e32 v125, v124, v123
	v_fma_f32 v126, -v122, v125, v124
	v_fmac_f32_e32 v125, v126, v123
	v_fma_f32 v122, -v122, v125, v124
	v_div_fmas_f32 v122, v122, v123, v125
	v_div_fixup_f32 v108, v122, v118, v78
	v_div_scale_f32 v122, s[72:73], v119, v119, v79
	v_rcp_f32_e32 v123, v122
	v_div_scale_f32 v124, vcc, v79, v119, v79
	v_fma_f32 v126, -v122, v123, 1.0
	v_fmac_f32_e32 v123, v126, v123
	v_mul_f32_e32 v125, v124, v123
	v_fma_f32 v126, -v122, v125, v124
	v_fmac_f32_e32 v125, v126, v123
	v_fma_f32 v122, -v122, v125, v124
	v_div_fmas_f32 v122, v122, v123, v125
	v_div_fixup_f32 v109, v122, v119, v79
	v_pk_mul_f32 v[70:71], v[108:109], v[70:71]
	v_cvt_pk_bf16_f32 v133, v70, v71
	v_pk_mul_f32 v[118:119], v[80:81], s[44:45]
	v_exp_f32_e32 v118, v118
	v_exp_f32_e32 v119, v119
	s_nop 0
	v_pk_add_f32 v[118:119], v[118:119], 1.0 op_sel_hi:[1,0]
	v_div_scale_f32 v122, s[72:73], v118, v118, v80
	v_rcp_f32_e32 v123, v122
	v_div_scale_f32 v124, vcc, v80, v118, v80
	v_fma_f32 v126, -v122, v123, 1.0
	v_fmac_f32_e32 v123, v126, v123
	v_mul_f32_e32 v125, v124, v123
	v_fma_f32 v126, -v122, v125, v124
	v_fmac_f32_e32 v125, v126, v123
	v_fma_f32 v122, -v122, v125, v124
	v_div_fmas_f32 v122, v122, v123, v125
	v_div_fixup_f32 v108, v122, v118, v80
	v_div_scale_f32 v122, s[72:73], v119, v119, v81
	v_rcp_f32_e32 v123, v122
	v_div_scale_f32 v124, vcc, v81, v119, v81
	v_fma_f32 v126, -v122, v123, 1.0
	v_fmac_f32_e32 v123, v126, v123
	v_mul_f32_e32 v125, v124, v123
	v_fma_f32 v126, -v122, v125, v124
	v_fmac_f32_e32 v125, v126, v123
	v_fma_f32 v122, -v122, v125, v124
	v_div_fmas_f32 v122, v122, v123, v125
	v_div_fixup_f32 v109, v122, v119, v81
	v_pk_mul_f32 v[72:73], v[108:109], v[72:73]
	v_cvt_pk_bf16_f32 v134, v72, v73
	v_pk_mul_f32 v[118:119], v[82:83], s[44:45]
	v_exp_f32_e32 v118, v118
	v_exp_f32_e32 v119, v119
	s_nop 0
	v_pk_add_f32 v[118:119], v[118:119], 1.0 op_sel_hi:[1,0]
	v_div_scale_f32 v122, s[72:73], v118, v118, v82
	v_rcp_f32_e32 v123, v122
	v_div_scale_f32 v124, vcc, v82, v118, v82
	v_fma_f32 v126, -v122, v123, 1.0
	v_fmac_f32_e32 v123, v126, v123
	v_mul_f32_e32 v125, v124, v123
	v_fma_f32 v126, -v122, v125, v124
	v_fmac_f32_e32 v125, v126, v123
	v_fma_f32 v122, -v122, v125, v124
	v_div_fmas_f32 v122, v122, v123, v125
	v_div_fixup_f32 v108, v122, v118, v82
	v_div_scale_f32 v122, s[72:73], v119, v119, v83
	v_rcp_f32_e32 v123, v122
	v_div_scale_f32 v124, vcc, v83, v119, v83
	v_fma_f32 v126, -v122, v123, 1.0
	v_fmac_f32_e32 v123, v126, v123
	v_mul_f32_e32 v125, v124, v123
	v_fma_f32 v126, -v122, v125, v124
	v_fmac_f32_e32 v125, v126, v123
	v_fma_f32 v122, -v122, v125, v124
	v_div_fmas_f32 v122, v122, v123, v125
	v_div_fixup_f32 v109, v122, v119, v83
	v_pk_mul_f32 v[74:75], v[108:109], v[74:75]
	v_cvt_pk_bf16_f32 v135, v74, v75
	global_store_dwordx4 v4, v[132:135], s[60:61]
	s_cmpk_lt_i32 s12, 0x100
	s_cbranch_scc1 .Lfm_loop
